# remove grid barrier between P9 (sample-row reduction, moved to workgroups 64-127, release+counter) and P10 (acquire before first sample tile)
# speedup vs baseline: 1.0139x; 1.0139x over previous
.LBB0_1041:
	s_or_b64 exec, exec, s[4:5]
	v_readlane_b32 s0, v255, 19
	v_readlane_b32 s1, v255, 20
	s_waitcnt lgkmcnt(0)
	v_mov_b32_e32 v0, v252
	v_readlane_b32 s92, v255, 18
	s_nop 1
	s_sub_i32 s92, s92, 0x200
	s_cmp_lt_u32 s92, 0x200
	s_cselect_b64 vcc, exec, 0
	s_barrier
	s_cbranch_vccz .LBB0_1086
	s_load_dwordx4 s[12:15], s[80:81], 0xc8
	s_load_dwordx4 s[16:19], s[80:81], 0x98
	v_lshlrev_b32_e32 v1, 2, v0
	v_and_b32_e32 v2, 0xfc, v1
	v_mov_b32_e32 v5, 0
	v_lshlrev_b32_e32 v4, 1, v2
	v_mbcnt_hi_u32_b32 v1, -1, v253
	s_waitcnt lgkmcnt(0)
	v_lshl_add_u64 v[6:7], s[14:15], 0, v[4:5]
	v_lshlrev_b32_e32 v4, 2, v2
	v_and_b32_e32 v3, 64, v1
	v_lshl_add_u64 v[8:9], s[14:15], 0, v[4:5]
	v_lshl_add_u64 v[36:37], s[16:17], 0, v[4:5]
	v_lshl_add_u64 v[38:39], s[12:13], 0, v[4:5]
	v_lshl_add_u64 v[40:41], s[18:19], 0, v[4:5]
	v_add_u32_e32 v3, 64, v3
	v_xor_b32_e32 v4, 1, v1
	v_cmp_lt_i32_e32 vcc, v4, v3
	s_add_u32 s0, s12, 0x8000000
	s_addc_u32 s1, s13, 0
	v_cndmask_b32_e32 v4, v1, v4, vcc
	v_lshlrev_b32_e32 v82, 2, v4
	v_xor_b32_e32 v4, 2, v1
	v_cmp_lt_i32_e32 vcc, v4, v3
	s_cmp_lg_u64 s[18:19], 0
	s_mov_b32 s6, s92
	v_cndmask_b32_e32 v4, v1, v4, vcc
	v_lshlrev_b32_e32 v83, 2, v4
	v_xor_b32_e32 v4, 4, v1
	v_cmp_lt_i32_e32 vcc, v4, v3
	s_cselect_b64 s[4:5], -1, 0
	s_add_i32 s10, s6, 0x8000
	v_cndmask_b32_e32 v4, v1, v4, vcc
	v_lshlrev_b32_e32 v84, 2, v4
	v_xor_b32_e32 v4, 8, v1
	v_cmp_lt_i32_e32 vcc, v4, v3
	s_mov_b64 s[8:9], 0x1d600000
	v_lshl_add_u64 v[34:35], v[8:9], 0, s[8:9]
	v_cndmask_b32_e32 v4, v1, v4, vcc
	v_lshlrev_b32_e32 v85, 2, v4
	v_xor_b32_e32 v4, 16, v1
	v_cmp_lt_i32_e32 vcc, v4, v3
	s_mov_b64 s[8:9], 0x2f00000
	s_ashr_i32 s11, s10, 31
	v_cndmask_b32_e32 v4, v1, v4, vcc
	v_lshl_add_u64 v[42:43], v[6:7], 0, s[8:9]
	v_lshlrev_b32_e32 v86, 2, v4
	v_xor_b32_e32 v4, 32, v1
	s_lshl_b64 s[8:9], s[10:11], 11
	v_cmp_lt_i32_e32 vcc, v4, v3
	v_and_b32_e32 v3, 63, v0
	s_add_u32 s8, s14, s8
	v_cndmask_b32_e32 v1, v1, v4, vcc
	v_lshlrev_b32_e32 v4, 3, v3
	s_addc_u32 s9, s15, s9
	s_mov_b64 s[6:7], 0x7000000
	v_lshlrev_b32_e32 v87, 2, v1
	v_lshl_add_u64 v[0:1], s[8:9], 0, v[4:5]
	s_ashr_i32 s83, s82, 31
	v_lshl_add_u64 v[32:33], v[6:7], 0, s[6:7]
	v_lshl_add_u64 v[44:45], v[0:1], 0, s[6:7]
	s_lshl_b64 s[14:15], s[82:83], 11
	s_lshl_b64 s[6:7], s[10:11], 12
	s_add_u32 s6, s12, s6
	v_lshlrev_b32_e32 v4, 4, v3
	s_addc_u32 s7, s13, s7
	v_lshl_add_u64 v[0:1], s[6:7], 0, v[4:5]
	s_mov_b64 s[6:7], 0xc00
	s_mov_b32 s17, 0
	v_lshl_add_u64 v[46:47], v[0:1], 0, s[6:7]
	s_lshl_b64 s[18:19], s[82:83], 12
	v_lshlrev_b32_e32 v88, 2, v2
	v_mov_b32_e32 v89, 0x358637bd
	s_mov_b32 s24, 0xfbf00000
	s_mov_b32 s25, 0xfbf01000
	s_branch .LBB0_1044

.LBB0_1086:
	s_waitcnt vmcnt(0)
	v_readlane_b32 s4, v255, 6
	v_readlane_b32 s5, v255, 7
	s_barrier
	s_and_saveexec_b64 s[0:1], s[4:5]
	s_xor_b64 s[4:5], exec, s[0:1]
	s_cbranch_execz .LBB0_1139
	s_cmp_lt_u32 s92, 0x200
	s_cbranch_scc0 .LBB0_1139
	buffer_wbl2 sc1
	s_waitcnt vmcnt(0)
	v_readlane_b32 s6, v255, 3
	v_readlane_b32 s7, v255, 4
	v_mov_b32_e32 v0, 0
	v_mov_b32_e32 v1, 1
	s_nop 4
	global_atomic_add v0, v1, s[6:7] offset:32
	s_waitcnt vmcnt(0)

.LBB0_1145:
	s_add_i32 s37, s37, 1
	s_cmp_lg_u32 s37, 8
	s_cbranch_scc1 .Lp10_noacq
	s_and_b32 s94, s2, 7
	s_cmp_lg_u32 s94, 7
	s_cbranch_scc1 .Lp10_noacq
	v_readlane_b32 s92, v255, 3
	v_readlane_b32 s93, v255, 4
	v_mov_b32_e32 v226, 0
	s_mov_b32 s95, 0
	s_nop 4
.Lp10_poll:
	global_load_dword v227, v226, s[92:93] offset:32 sc1
	s_waitcnt vmcnt(0)
	v_readfirstlane_b32 s94, v227
	s_cmp_ge_u32 s94, 64
	s_cbranch_scc1 .Lp10_acq
	s_add_u32 s95, s95, 1
	s_cmp_gt_u32 s95, 4000
	s_cbranch_scc1 .Lp10_acq
	s_sleep 2
	s_branch .Lp10_poll

.Lp10_noacq:
	s_mul_i32 s6, s37, s85
	s_mul_hi_u32 s7, s37, s84
	s_add_i32 s7, s7, s6
	s_mul_i32 s6, s37, s84
	s_add_u32 s18, s6, s2
	s_addc_u32 s19, s7, s3
	v_cmp_gt_i64_e32 vcc, s[18:19], v[142:143]
	v_cmp_lt_i64_e64 s[6:7], s[18:19], v[140:141]
	s_cbranch_vccnz .LBB0_1151
	s_ashr_i32 s14, s18, 31
	s_lshr_b32 s14, s14, 29
	s_add_i32 s16, s18, s14
	s_and_b32 s14, s16, -8
	s_sub_i32 s17, s18, s14
	s_cmp_gt_i32 s17, 3
	s_mov_b64 s[14:15], -1
	s_cbranch_scc0 .LBB0_1148
	s_mul_i32 s14, s17, 0x165
	s_add_i32 s18, s14, 4
	s_mov_b64 s[14:15], 0
